# v53 with finer PLE distribution in P3b: pool WGs with 2 pool-GEMM units 3 PLE units, with 1 unit 3-4, three-sample WGs 1, scan WGs 2
# speedup vs baseline: 1.0113x; 1.0113x over previous
.LBB0_961:
	s_cmpk_gt_i32 s66, 0x29f
	v_mbcnt_lo_u32_b32 v8, -1, 0
	v_mbcnt_hi_u32_b32 v8, -1, v8
	s_nop 0
	s_cbranch_scc1 .LBB0_978
	s_cmp_eq_u32 s98, 1
	s_cbranch_scc1 .Lple_go
	s_mov_b32 s99, s40
	s_movk_i32 s100, 0x240
	s_cmpk_lg_i32 s88, 0x100
	s_cbranch_scc1 .Lple_go
	s_cmpk_lt_i32 s40, 64
	s_cbranch_scc1 .Lple_c3
	s_sub_i32 s40, s40, 64
	s_movk_i32 s7, 48
	s_movk_i32 s100, 0x90
	s_cmpk_lt_i32 s40, 48
	s_cbranch_scc1 .Lple_go
	s_add_i32 s40, s40, 0x60
	s_movk_i32 s100, 0x140
	s_branch .Lple_go
.Lple_c3:
	s_add_i32 s40, s40, 0x140
	s_movk_i32 s7, 0x100
	s_movk_i32 s100, 0x180
